# attention QK^T: K-fragment ds_reads two steps ahead of MFMAs with counted lgkmcnt (second fragment set v240-247), on top of deferred PV for waves 4-7
# baseline (speedup 1.0000x reference)
; __device__ __forceinline__ void qkt(f32x16& p0, f32x16& p1, const char* Ks, const bf16x8* qr, int r32, int hi) {
;   p0 = f32x16{}; p1 = f32x16{};
; #pragma unroll
;   for (int d0 = 0; d0 < 8; ++d0) { int cb = (d0 * 16 + hi * 8) * 2;
;     bf16x8 b0 = *reinterpret_cast<const bf16x8*>(Ks + KSWZ(r32, cb));
;     bf16x8 b1 = *reinterpret_cast<const bf16x8*>(Ks + KSWZ(32 + r32, cb));
;     p0 = __builtin_amdgcn_mfma_f32_32x32x16_bf16(b0, qr[d0], p0, 0, 0, 0);
;     p1 = __builtin_amdgcn_mfma_f32_32x32x16_bf16(b1, qr[d0], p1, 0, 0, 0); }
; __device__ __forceinline__ void score_xform(f32x16& p0, f32x16& p1, float sl, float base, bool mask, int kp0, int t, int tlo) {
;   const float s2_ = sl + sl, s4_ = s2_ + s2_, s8_ = s4_ + s4_;
;   const float a_[4] = {0.f, sl, s2_, s2_ + sl};
;   float b_[8]; b_[0] = base;
; #pragma unroll
;   for (int q = 1; q < 8; ++q) b_[q] = b_[q - 1] + s8_;
; #pragma unroll
;   for (int r = 0; r < 16; ++r) { p0[r] = fmaf(p0[r], CSC, a_[r & 3] + b_[r >> 2]); p1[r] = fmaf(p1[r], CSC, a_[r & 3] + b_[4 + (r >> 2)]); }
.LBB0_871:
	s_add_i32 s4, s83, s9
	s_add_i32 m0, s4, 0xa000
	s_add_i32 s4, s8, 0
	global_load_lds_dwordx4 v[68:69], off
	v_add_u32_e32 v2, s4, v182
	ds_read_b128 v[68:71], v2
	ds_read_b128 v[72:75], v2 offset:8192
	v_add_u32_e32 v2, s4, v183
	ds_read_b128 v[164:167], v2
	ds_read_b128 v[168:171], v2 offset:8192
	v_add_u32_e32 v2, s4, v184
	ds_read_b128 v[240:243], v2
	ds_read_b128 v[244:247], v2 offset:8192
	v_lshl_add_u32 v199, s6, 6, v189
	s_cmp_lg_u32 s6, s85
	s_waitcnt lgkmcnt(4)
	v_mfma_f32_32x32x16_bf16 v[84:99], v[68:71], v[104:107], 0
	v_add_u32_e32 v2, s4, v185
	v_mfma_f32_32x32x16_bf16 v[68:83], v[72:75], v[104:107], 0
	s_waitcnt lgkmcnt(2)
	v_mfma_f32_32x32x16_bf16 v[84:99], v[164:167], v[108:111], v[84:99]
	v_mfma_f32_32x32x16_bf16 v[68:83], v[168:171], v[108:111], v[68:83]
	ds_read_b128 v[164:167], v2
	ds_read_b128 v[168:171], v2 offset:8192
	v_add_u32_e32 v2, s4, v186
	s_waitcnt lgkmcnt(2)
	v_mfma_f32_32x32x16_bf16 v[84:99], v[240:243], v[112:115], v[84:99]
	v_mfma_f32_32x32x16_bf16 v[68:83], v[244:247], v[112:115], v[68:83]
	ds_read_b128 v[240:243], v2
	ds_read_b128 v[244:247], v2 offset:8192
	v_add_u32_e32 v2, s4, v187
	s_waitcnt lgkmcnt(2)
	v_mfma_f32_32x32x16_bf16 v[84:99], v[164:167], v[116:119], v[84:99]
	v_mfma_f32_32x32x16_bf16 v[68:83], v[168:171], v[116:119], v[68:83]
	ds_read_b128 v[164:167], v2
	ds_read_b128 v[168:171], v2 offset:8192
	v_add_u32_e32 v2, s4, v188
	s_waitcnt lgkmcnt(2)
	v_mfma_f32_32x32x16_bf16 v[84:99], v[240:243], v[120:123], v[84:99]
	v_mfma_f32_32x32x16_bf16 v[68:83], v[244:247], v[120:123], v[68:83]
	ds_read_b128 v[240:243], v2
	ds_read_b128 v[244:247], v2 offset:8192
	v_add_u32_e32 v2, s4, v190
	s_waitcnt lgkmcnt(2)
	v_mfma_f32_32x32x16_bf16 v[84:99], v[164:167], v[124:127], v[84:99]
	v_mfma_f32_32x32x16_bf16 v[68:83], v[168:171], v[124:127], v[68:83]
	ds_read_b128 v[164:167], v2
	ds_read_b128 v[168:171], v2 offset:8192
	s_waitcnt lgkmcnt(2)
	v_mfma_f32_32x32x16_bf16 v[84:99], v[240:243], v[128:131], v[84:99]
	v_mfma_f32_32x32x16_bf16 v[68:83], v[244:247], v[128:131], v[68:83]
	v_bfe_u32 v2, v196, s6, 1
	v_cmp_eq_u32_e32 vcc, 0, v2
	v_sub_u32_e32 v2, v199, v181
	v_cvt_f32_i32_e32 v2, v2
	s_waitcnt lgkmcnt(0)
	v_mfma_f32_32x32x16_bf16 v[84:99], v[164:167], v[132:135], v[84:99]
	v_cndmask_b32_e32 v166, 0, v174, vcc
	v_fmac_f32_e32 v166, v141, v2
	v_mov_b32_e32 v2, v166
	v_add_f32_e64 v164, v146, v166
	v_add_f32_e64 v165, v147, v166
	v_mfma_f32_32x32x16_bf16 v[68:83], v[168:171], v[132:135], v[68:83]
	s_nop 5
	v_fmac_f32_e32 v2, 0x3e0293ee, v84
	v_mov_b32_e32 v84, v85
	v_mov_b32_e32 v85, v86
	v_fma_f32 v164, v84, s90, v164
	v_fma_f32 v165, v85, s90, v165
	v_pk_add_f32 v[84:85], v[144:145], v[166:167] op_sel_hi:[1,0]
	v_mov_b32_e32 v86, v87
	v_mov_b32_e32 v87, v88
	v_pk_fma_f32 v[166:167], v[86:87], s[90:91], v[84:85] op_sel_hi:[1,0,1]
	v_pk_add_f32 v[86:87], v[146:147], v[84:85] op_sel:[0,1]
	v_mov_b32_e32 v88, v89
	v_mov_b32_e32 v89, v90
	v_pk_add_f32 v[84:85], v[144:145], v[84:85] op_sel:[0,1]
	v_pk_fma_f32 v[168:169], v[88:89], s[90:91], v[86:87] op_sel_hi:[1,0,1]
	v_mov_b32_e32 v86, v91
	v_mov_b32_e32 v87, v92
	v_pk_add_f32 v[200:201], v[144:145], v[84:85] op_sel:[0,1]
	v_pk_fma_f32 v[170:171], v[86:87], s[90:91], v[84:85] op_sel_hi:[1,0,1]
	v_pk_add_f32 v[86:87], v[146:147], v[84:85] op_sel:[0,1]
	v_mov_b32_e32 v88, v93
	v_mov_b32_e32 v89, v94
	v_pk_add_f32 v[84:85], v[144:145], v[200:201]
	v_pk_fma_f32 v[92:93], v[88:89], s[90:91], v[86:87] op_sel_hi:[1,0,1]
	v_add_f32_e32 v87, v141, v85
	v_mov_b32_e32 v86, v85
	v_pk_add_f32 v[202:203], v[144:145], v[84:85]
	v_pk_fma_f32 v[90:91], v[68:69], s[90:91], v[86:87] op_sel_hi:[1,0,1]
	v_pk_add_f32 v[68:69], v[142:143], v[84:85] op_sel:[0,1]
	v_pk_add_f32 v[204:205], v[144:145], v[202:203]
	v_pk_fma_f32 v[88:89], v[70:71], s[90:91], v[68:69] op_sel_hi:[1,0,1]
	v_pk_add_f32 v[68:69], v[140:141], v[202:203] op_sel:[0,1]
	s_nop 0
	v_pk_fma_f32 v[86:87], v[72:73], s[90:91], v[68:69] op_sel_hi:[1,0,1]
	v_pk_add_f32 v[68:69], v[142:143], v[202:203] op_sel:[0,1]
	s_nop 0
	v_pk_fma_f32 v[84:85], v[74:75], s[90:91], v[68:69] op_sel_hi:[1,0,1]
	v_pk_add_f32 v[68:69], v[140:141], v[204:205] op_sel:[0,1]
	v_add_f32_e32 v74, v145, v205
	v_pk_fma_f32 v[70:71], v[76:77], s[90:91], v[68:69] op_sel_hi:[1,0,1]
	v_mov_b32_e32 v68, v95
	v_mov_b32_e32 v69, v96
	v_pk_fma_f32 v[76:77], v[68:69], s[90:91], v[200:201] op_sel_hi:[1,0,1]
	v_pk_add_f32 v[68:69], v[142:143], v[204:205] op_sel:[0,1]
	s_nop 0
	v_pk_fma_f32 v[72:73], v[78:79], s[90:91], v[68:69] op_sel_hi:[1,0,1]
	v_pk_add_f32 v[68:69], v[140:141], v[74:75] op_sel_hi:[1,0]
	v_pk_add_f32 v[78:79], v[146:147], v[200:201] op_sel:[0,1]
	v_pk_fma_f32 v[68:69], v[80:81], s[90:91], v[68:69] op_sel_hi:[1,0,1]
	v_mov_b32_e32 v80, v97
	v_mov_b32_e32 v81, v98
	v_pk_fma_f32 v[78:79], v[80:81], s[90:91], v[78:79] op_sel_hi:[1,0,1]
	v_add_f32_e32 v80, v144, v201
	v_pk_add_f32 v[74:75], v[142:143], v[74:75] op_sel_hi:[1,0]
	v_fmac_f32_e32 v80, 0x3e0293ee, v99
	v_pk_fma_f32 v[74:75], v[82:83], s[90:91], v[74:75] op_sel_hi:[1,0,1]
	s_cbranch_scc1 .LBB0_873
; __device__ __forceinline__ void score_xform(f32x16& p0, f32x16& p1, float sl, float base, bool mask, int kp0, int t, int tlo) {
;     ...
;   if (mask) {
;     const int dhi = t - kp0, dlo = tlo - kp0;
; #pragma unroll
;     for (int r = 0; r < 16; ++r) { const int c = (r & 3) + 8 * (r >> 2);
;       p0[r] = (c > dhi || c < dlo) ? -1e30f : p0[r]; p1[r] = (c + 32 > dhi || c + 32 < dlo) ? -1e30f : p1[r]; } }
	v_sub_u32_e32 v81, v181, v199
	v_or_b32_e32 v82, v81, v199
	v_cmp_lt_i32_e32 vcc, -1, v82
	v_cmp_gt_i32_e64 s[6:7], 1, v81
	v_cmp_gt_i32_e64 s[4:5], -2, v199
	v_cndmask_b32_e32 v2, v174, v2, vcc
	v_cmp_gt_i32_e32 vcc, -1, v199
	v_cmp_gt_i32_e64 s[8:9], 2, v81
	s_or_b64 vcc, vcc, s[6:7]
	v_cndmask_b32_e32 v164, v164, v174, vcc
	s_or_b64 vcc, s[4:5], s[8:9]
	v_cndmask_b32_e32 v165, v165, v174, vcc
	v_cmp_gt_i32_e32 vcc, -3, v199
	v_cmp_gt_i32_e64 s[6:7], 3, v81
	v_cmp_gt_i32_e64 s[4:5], -8, v199
	v_cmp_gt_i32_e64 s[8:9], 8, v81
	s_or_b64 vcc, vcc, s[6:7]
	v_cndmask_b32_e32 v166, v166, v174, vcc
	s_or_b64 vcc, s[4:5], s[8:9]
	v_cndmask_b32_e32 v167, v167, v174, vcc
	v_cmp_gt_i32_e32 vcc, -9, v199
	v_cmp_gt_i32_e64 s[6:7], 9, v81
	v_cmp_gt_i32_e64 s[4:5], -10, v199
	v_cmp_gt_i32_e64 s[8:9], 10, v81
	s_or_b64 vcc, vcc, s[6:7]
	v_cndmask_b32_e32 v168, v168, v174, vcc
	s_or_b64 vcc, s[4:5], s[8:9]
	v_cndmask_b32_e32 v169, v169, v174, vcc
	v_cmp_gt_i32_e32 vcc, -11, v199
	v_cmp_gt_i32_e64 s[6:7], 11, v81
	v_cmp_gt_i32_e64 s[4:5], -16, v199
	v_cmp_gt_i32_e64 s[8:9], 16, v81
	s_or_b64 vcc, vcc, s[6:7]
	v_cndmask_b32_e32 v170, v170, v174, vcc
	s_or_b64 vcc, s[4:5], s[8:9]
	s_movk_i32 s4, 0xffef
	v_cndmask_b32_e32 v171, v171, v174, vcc
	v_cmp_gt_i32_e32 vcc, s4, v199
	s_movk_i32 s4, 0xffee
	v_cmp_gt_i32_e64 s[6:7], 17, v81
	v_cmp_gt_i32_e64 s[4:5], s4, v199
	v_cmp_gt_i32_e64 s[8:9], 18, v81
	s_or_b64 vcc, vcc, s[6:7]
	v_cndmask_b32_e32 v92, v92, v174, vcc
	s_or_b64 vcc, s[4:5], s[8:9]
	s_movk_i32 s4, 0xffed
	v_cndmask_b32_e32 v93, v93, v174, vcc
	v_cmp_gt_i32_e32 vcc, s4, v199
	s_movk_i32 s4, 0xffe8
	v_cmp_gt_i32_e64 s[6:7], 19, v81
	v_cmp_gt_i32_e64 s[4:5], s4, v199
	v_cmp_gt_i32_e64 s[8:9], 24, v81
	s_or_b64 vcc, vcc, s[6:7]
	v_cndmask_b32_e32 v76, v76, v174, vcc
	s_or_b64 vcc, s[4:5], s[8:9]
	s_movk_i32 s4, 0xffe7
	v_cndmask_b32_e32 v77, v77, v174, vcc
	v_cmp_gt_i32_e32 vcc, s4, v199
	s_movk_i32 s4, 0xffe6
	v_cmp_gt_i32_e64 s[6:7], 25, v81
	v_cmp_gt_i32_e64 s[4:5], s4, v199
	v_cmp_gt_i32_e64 s[8:9], 26, v81
	s_or_b64 vcc, vcc, s[6:7]
	v_cndmask_b32_e32 v78, v78, v174, vcc
	s_or_b64 vcc, s[4:5], s[8:9]
	s_movk_i32 s4, 0xffe5
	v_cndmask_b32_e32 v79, v79, v174, vcc
	v_cmp_gt_i32_e32 vcc, 27, v81
	v_cmp_gt_i32_e64 s[4:5], s4, v199
	s_or_b64 vcc, s[4:5], vcc
	s_movk_i32 s4, 0xffe0
	v_cndmask_b32_e32 v80, v80, v174, vcc
	v_cmp_gt_i32_e32 vcc, s4, v199
	s_movk_i32 s4, 0xffdf
	v_cmp_gt_i32_e64 s[36:37], 32, v81
	v_cmp_gt_i32_e64 s[4:5], s4, v199
	s_movk_i32 s6, 0xffde
	v_cmp_gt_i32_e64 s[38:39], 33, v81
	s_or_b64 vcc, vcc, s[36:37]
	v_cmp_gt_i32_e64 s[6:7], s6, v199
	s_movk_i32 s8, 0xffdd
	v_cmp_gt_i32_e64 s[40:41], 34, v81
	v_cndmask_b32_e32 v90, v90, v174, vcc
	s_or_b64 vcc, s[4:5], s[38:39]
	v_cmp_gt_i32_e64 s[8:9], s8, v199
	s_movk_i32 s10, 0xffd8
	v_cmp_gt_i32_e64 s[42:43], 35, v81
	v_cndmask_b32_e32 v91, v91, v174, vcc
	s_or_b64 vcc, s[6:7], s[40:41]
	v_cmp_gt_i32_e64 s[10:11], s10, v199
	s_movk_i32 s12, 0xffd7
	v_cmp_gt_i32_e64 s[44:45], 40, v81
	v_cndmask_b32_e32 v88, v88, v174, vcc
	s_or_b64 vcc, s[8:9], s[42:43]
	v_cmp_gt_i32_e64 s[12:13], s12, v199
	s_movk_i32 s14, 0xffd6
	v_cmp_gt_i32_e64 s[46:47], 41, v81
	v_cndmask_b32_e32 v89, v89, v174, vcc
	s_or_b64 vcc, s[10:11], s[44:45]
	v_cmp_gt_i32_e64 s[14:15], s14, v199
	s_movk_i32 s16, 0xffd5
	v_cmp_gt_i32_e64 s[48:49], 42, v81
	v_cndmask_b32_e32 v86, v86, v174, vcc
	s_or_b64 vcc, s[12:13], s[46:47]
	v_cmp_gt_i32_e64 s[16:17], s16, v199
	s_movk_i32 s18, 0xffd0
	v_cmp_gt_i32_e64 s[50:51], 43, v81
	v_cndmask_b32_e32 v87, v87, v174, vcc
	s_or_b64 vcc, s[14:15], s[48:49]
	v_cmp_gt_i32_e64 s[18:19], s18, v199
	s_movk_i32 s20, 0xffcf
	v_cmp_gt_i32_e64 s[52:53], 48, v81
	v_cndmask_b32_e32 v84, v84, v174, vcc
	s_or_b64 vcc, s[16:17], s[50:51]
	v_cmp_gt_i32_e64 s[20:21], s20, v199
	s_movk_i32 s22, 0xffce
	v_cmp_gt_i32_e64 s[54:55], 49, v81
	v_cndmask_b32_e32 v85, v85, v174, vcc
	s_or_b64 vcc, s[18:19], s[52:53]
	v_cmp_gt_i32_e64 s[22:23], s22, v199
	s_movk_i32 s24, 0xffcd
	v_cmp_gt_i32_e64 s[56:57], 50, v81
	v_cndmask_b32_e32 v70, v70, v174, vcc
	s_or_b64 vcc, s[20:21], s[54:55]
	v_cmp_gt_i32_e64 s[24:25], s24, v199
	s_movk_i32 s26, 0xffc8
	v_cmp_gt_i32_e64 s[58:59], 51, v81
	v_cndmask_b32_e32 v71, v71, v174, vcc
	s_or_b64 vcc, s[22:23], s[56:57]
	v_cmp_gt_i32_e64 s[26:27], s26, v199
	s_movk_i32 s28, 0xffc7
	v_cmp_gt_i32_e64 s[60:61], 56, v81
	v_cndmask_b32_e32 v72, v72, v174, vcc
	s_or_b64 vcc, s[24:25], s[58:59]
	v_cmp_gt_i32_e64 s[28:29], s28, v199
	s_movk_i32 s30, 0xffc6
	v_cmp_gt_i32_e64 s[62:63], 57, v81
	v_cndmask_b32_e32 v73, v73, v174, vcc
	s_or_b64 vcc, s[26:27], s[60:61]
	v_cmp_gt_i32_e64 s[30:31], s30, v199
	s_movk_i32 s34, 0xffc5
	v_cmp_gt_i32_e64 s[64:65], 58, v81
	v_cndmask_b32_e32 v68, v68, v174, vcc
	s_or_b64 vcc, s[28:29], s[62:63]
	v_cmp_gt_i32_e64 s[34:35], s34, v199
	v_cmp_gt_i32_e64 s[66:67], 59, v81
	v_cndmask_b32_e32 v69, v69, v174, vcc
	s_or_b64 vcc, s[30:31], s[64:65]
	v_cndmask_b32_e32 v74, v74, v174, vcc
	s_or_b64 vcc, s[34:35], s[66:67]
	v_cndmask_b32_e32 v75, v75, v174, vcc

; __device__ __forceinline__ void qkt(f32x16& p0, f32x16& p1, const char* Ks, const bf16x8* qr, int r32, int hi) {
;   p0 = f32x16{}; p1 = f32x16{};
; #pragma unroll
;   for (int d0 = 0; d0 < 8; ++d0) { int cb = (d0 * 16 + hi * 8) * 2;
;     bf16x8 b0 = *reinterpret_cast<const bf16x8*>(Ks + KSWZ(r32, cb));
;     bf16x8 b1 = *reinterpret_cast<const bf16x8*>(Ks + KSWZ(32 + r32, cb));
;     p0 = __builtin_amdgcn_mfma_f32_32x32x16_bf16(b0, qr[d0], p0, 0, 0, 0);
;     p1 = __builtin_amdgcn_mfma_f32_32x32x16_bf16(b1, qr[d0], p1, 0, 0, 0); }
; __device__ __forceinline__ void score_xform(f32x16& p0, f32x16& p1, float sl, float base, bool mask, int kp0, int t, int tlo) {
;   const float s2_ = sl + sl, s4_ = s2_ + s2_, s8_ = s4_ + s4_;
;   const float a_[4] = {0.f, sl, s2_, s2_ + sl};
;   float b_[8]; b_[0] = base;
; #pragma unroll
;   for (int q = 1; q < 8; ++q) b_[q] = b_[q - 1] + s8_;
; #pragma unroll
;   for (int r = 0; r < 16; ++r) { p0[r] = fmaf(p0[r], CSC, a_[r & 3] + b_[r >> 2]); p1[r] = fmaf(p1[r], CSC, a_[r & 3] + b_[4 + (r >> 2)]); }
.LBB0_887:
	s_add_i32 s4, s8, 0
	v_add_u32_e32 v2, s4, v182
	ds_read_b128 v[68:71], v2
	ds_read_b128 v[72:75], v2 offset:8192
	v_add_u32_e32 v2, s4, v183
	ds_read_b128 v[158:161], v2
	ds_read_b128 v[162:165], v2 offset:8192
	v_add_u32_e32 v2, s4, v184
	ds_read_b128 v[240:243], v2
	ds_read_b128 v[244:247], v2 offset:8192
	s_lshl_b32 s7, s6, 6
	s_cmp_eq_u32 s6, s85
	s_waitcnt lgkmcnt(4)
	v_mfma_f32_32x32x16_bf16 v[84:99], v[68:71], v[104:107], 0
	v_add_u32_e32 v2, s4, v185
	v_mfma_f32_32x32x16_bf16 v[68:83], v[72:75], v[104:107], 0
	s_waitcnt lgkmcnt(2)
	v_mfma_f32_32x32x16_bf16 v[84:99], v[158:161], v[108:111], v[84:99]
	v_mfma_f32_32x32x16_bf16 v[68:83], v[162:165], v[108:111], v[68:83]
	ds_read_b128 v[158:161], v2
	ds_read_b128 v[162:165], v2 offset:8192
	v_add_u32_e32 v2, s4, v186
	s_waitcnt lgkmcnt(2)
	v_mfma_f32_32x32x16_bf16 v[84:99], v[240:243], v[112:115], v[84:99]
	v_mfma_f32_32x32x16_bf16 v[68:83], v[244:247], v[112:115], v[68:83]
	ds_read_b128 v[240:243], v2
	ds_read_b128 v[244:247], v2 offset:8192
	v_add_u32_e32 v2, s4, v187
	s_waitcnt lgkmcnt(2)
	v_mfma_f32_32x32x16_bf16 v[84:99], v[158:161], v[116:119], v[84:99]
	v_mfma_f32_32x32x16_bf16 v[68:83], v[162:165], v[116:119], v[68:83]
	ds_read_b128 v[158:161], v2
	ds_read_b128 v[162:165], v2 offset:8192
	v_add_u32_e32 v2, s4, v188
	s_waitcnt lgkmcnt(2)
	v_mfma_f32_32x32x16_bf16 v[84:99], v[240:243], v[120:123], v[84:99]
	v_mfma_f32_32x32x16_bf16 v[68:83], v[244:247], v[120:123], v[68:83]
	ds_read_b128 v[240:243], v2
	ds_read_b128 v[244:247], v2 offset:8192
	v_add_u32_e32 v2, s4, v190
	s_waitcnt lgkmcnt(2)
	v_mfma_f32_32x32x16_bf16 v[84:99], v[158:161], v[124:127], v[84:99]
	v_mfma_f32_32x32x16_bf16 v[68:83], v[162:165], v[124:127], v[68:83]
	ds_read_b128 v[166:169], v2
	s_cselect_b64 s[4:5], -1, 0
	s_cmp_lt_i32 s7, s33
	s_waitcnt lgkmcnt(1)
	v_mfma_f32_32x32x16_bf16 v[84:99], v[240:243], v[128:131], v[84:99]
	v_add_u32_e32 v159, s7, v189
	s_cselect_b64 s[6:7], -1, 0
	s_or_b64 s[4:5], s[4:5], s[6:7]
	s_andn2_b64 vcc, exec, s[4:5]
	v_mfma_f32_32x32x16_bf16 v[68:83], v[244:247], v[128:131], v[68:83]
	ds_read_b128 v[160:163], v2 offset:8192
	v_sub_u32_e32 v2, v159, v181
	v_cvt_f32_i32_e32 v2, v2
	v_fma_f32 v164, v141, v2, 0
	s_waitcnt lgkmcnt(1)
	v_mfma_f32_32x32x16_bf16 v[84:99], v[166:169], v[132:135], v[84:99]
	v_add_f32_e32 v165, v141, v164
	s_waitcnt lgkmcnt(0)
	v_mfma_f32_32x32x16_bf16 v[68:83], v[160:163], v[132:135], v[68:83]
	s_nop 8
	v_fma_f32 v154, v84, s90, v164
	v_fma_f32 v155, v85, s90, v165
	v_add_f32_e64 v84, v142, v164
	v_add_f32_e64 v85, v143, v164
	v_fma_f32 v86, v86, s90, v84
	v_fma_f32 v87, v87, s90, v85
	v_add_f32_e32 v84, v145, v164
	v_add_f32_e32 v85, v141, v84
	v_pk_fma_f32 v[88:89], v[88:89], s[90:91], v[84:85] op_sel_hi:[1,0,1]
	v_pk_add_f32 v[162:163], v[142:143], v[84:85] op_sel_hi:[1,0]
	v_add_f32_e32 v84, v145, v84
	v_add_f32_e32 v85, v141, v84
	v_mov_b32_e32 v161, v72
	v_mov_b32_e32 v72, v73
	v_mov_b32_e32 v73, v74
	v_pk_fma_f32 v[90:91], v[90:91], s[90:91], v[162:163] op_sel_hi:[1,0,1]
	v_mov_b32_e32 v74, v75
	v_mov_b32_e32 v75, v76
	v_mov_b32_e32 v162, v77
	v_pk_add_f32 v[76:77], v[142:143], v[84:85] op_sel_hi:[1,0]
	v_add_f32_e32 v166, v145, v84
	v_pk_fma_f32 v[94:95], v[94:95], s[90:91], v[76:77] op_sel_hi:[1,0,1]
	v_add_f32_e32 v76, v145, v166
	v_add_f32_e32 v77, v141, v76
	v_mov_b32_e32 v160, v71
	v_pk_fma_f32 v[92:93], v[92:93], s[90:91], v[84:85] op_sel_hi:[1,0,1]
	v_pk_fma_f32 v[84:85], v[68:69], s[90:91], v[76:77] op_sel_hi:[1,0,1]
	v_add_f32_e32 v158, v142, v76
	v_pk_add_f32 v[68:69], v[144:145], v[76:77] op_sel_hi:[1,0]
	v_fmac_f32_e32 v158, 0x3e0293ee, v70
	v_pk_fma_f32 v[76:77], v[160:161], s[90:91], v[68:69] op_sel_hi:[1,0,1]
	v_pk_add_f32 v[70:71], v[146:147], v[68:69] op_sel:[0,1]
	v_mov_b32_e32 v2, v69
	v_pk_add_f32 v[68:69], v[144:145], v[68:69]
	v_pk_fma_f32 v[72:73], v[72:73], s[90:91], v[70:71] op_sel_hi:[1,0,1]
	v_mov_b32_e32 v70, v144
	v_mov_b32_e32 v71, v69
	v_pk_add_f32 v[70:71], v[70:71], v[2:3]
	v_mov_b32_e32 v163, v78
	v_mov_b32_e32 v164, v79
	v_pk_add_f32 v[160:161], v[144:145], v[68:69]
	v_pk_fma_f32 v[78:79], v[74:75], s[90:91], v[70:71] op_sel_hi:[1,0,1]
	v_pk_add_f32 v[70:71], v[146:147], v[68:69] op_sel:[0,1]
	v_mov_b32_e32 v165, v80
	v_add_f32_e32 v167, v141, v166
	v_pk_fma_f32 v[74:75], v[162:163], s[90:91], v[70:71] op_sel_hi:[1,0,1]
	v_mov_b32_e32 v68, v69
	v_mov_b32_e32 v69, v161
	v_pk_add_f32 v[70:71], v[146:147], v[160:161] op_sel:[0,1]
	v_mov_b32_e32 v80, v81
	v_mov_b32_e32 v81, v82
	v_pk_add_f32 v[68:69], v[152:153], v[68:69]
	v_pk_fma_f32 v[70:71], v[80:81], s[90:91], v[70:71] op_sel_hi:[1,0,1]
	v_pk_add_f32 v[80:81], v[142:143], v[166:167] op_sel_hi:[1,0]
	v_add_f32_e32 v2, v144, v161
	v_pk_fma_f32 v[96:97], v[96:97], s[90:91], v[166:167] op_sel_hi:[1,0,1]
	v_pk_fma_f32 v[68:69], v[164:165], s[90:91], v[68:69] op_sel_hi:[1,0,1]
	v_pk_fma_f32 v[80:81], v[98:99], s[90:91], v[80:81] op_sel_hi:[1,0,1]
	v_fmac_f32_e32 v2, 0x3e0293ee, v83
	s_cbranch_vccnz .LBB0_889
; __device__ __forceinline__ void score_xform(f32x16& p0, f32x16& p1, float sl, float base, bool mask, int kp0, int t, int tlo) {
;     ...
;   if (mask) {
;     const int dhi = t - kp0, dlo = tlo - kp0;
; #pragma unroll
;     for (int r = 0; r < 16; ++r) { const int c = (r & 3) + 8 * (r >> 2);
;       p0[r] = (c > dhi || c < dlo) ? -1e30f : p0[r]; p1[r] = (c + 32 > dhi || c + 32 < dlo) ? -1e30f : p1[r]; } }
	v_sub_u32_e32 v82, v181, v159
	v_sub_u32_e32 v83, v140, v159
	v_cmp_gt_i32_e32 vcc, 0, v82
	v_cmp_lt_i32_e64 s[4:5], 0, v83
	s_or_b64 vcc, vcc, s[4:5]
	v_cndmask_b32_e32 v154, v154, v174, vcc
	v_cmp_gt_i32_e32 vcc, 32, v82
	v_cmp_lt_i32_e64 s[4:5], 32, v83
	s_or_b64 vcc, vcc, s[4:5]
	v_cndmask_b32_e32 v84, v84, v174, vcc
	v_cmp_gt_i32_e32 vcc, 1, v82
	v_cmp_lt_i32_e64 s[4:5], 1, v83
	s_or_b64 vcc, vcc, s[4:5]
	v_cndmask_b32_e32 v155, v155, v174, vcc
	v_cmp_gt_i32_e32 vcc, 33, v82
	v_cmp_lt_i32_e64 s[4:5], 33, v83
	s_or_b64 vcc, vcc, s[4:5]
	v_cndmask_b32_e32 v85, v85, v174, vcc
	v_cmp_gt_i32_e32 vcc, 2, v82
	v_cmp_lt_i32_e64 s[4:5], 2, v83
	s_or_b64 vcc, vcc, s[4:5]
	v_cndmask_b32_e32 v86, v86, v174, vcc
	v_cmp_gt_i32_e32 vcc, 34, v82
	v_cmp_lt_i32_e64 s[4:5], 34, v83
	s_or_b64 vcc, vcc, s[4:5]
	v_cndmask_b32_e32 v158, v158, v174, vcc
	v_cmp_gt_i32_e32 vcc, 3, v82
	v_cmp_lt_i32_e64 s[4:5], 3, v83
	s_or_b64 vcc, vcc, s[4:5]
	v_cndmask_b32_e32 v87, v87, v174, vcc
	v_cmp_gt_i32_e32 vcc, 8, v82
	v_cmp_lt_i32_e64 s[4:5], 8, v83
	s_or_b64 vcc, vcc, s[4:5]
	v_cndmask_b32_e32 v88, v88, v174, vcc
	v_cmp_gt_i32_e32 vcc, 35, v82
	v_cmp_lt_i32_e64 s[6:7], 35, v83
	v_cmp_gt_i32_e64 s[4:5], 40, v82
	v_cmp_lt_i32_e64 s[8:9], 40, v83
	s_or_b64 vcc, vcc, s[6:7]
	v_cndmask_b32_e32 v76, v76, v174, vcc
	s_or_b64 vcc, s[4:5], s[8:9]
	v_cndmask_b32_e32 v77, v77, v174, vcc
	v_cmp_gt_i32_e32 vcc, 9, v82
	v_cmp_lt_i32_e64 s[4:5], 9, v83
	s_or_b64 vcc, vcc, s[4:5]
	v_cndmask_b32_e32 v89, v89, v174, vcc
	v_cmp_gt_i32_e32 vcc, 41, v82
	v_cmp_lt_i32_e64 s[4:5], 41, v83
	s_or_b64 vcc, vcc, s[4:5]
	v_cndmask_b32_e32 v72, v72, v174, vcc
	v_cmp_gt_i32_e32 vcc, 10, v82
	v_cmp_lt_i32_e64 s[4:5], 10, v83
	s_or_b64 vcc, vcc, s[4:5]
	v_cndmask_b32_e32 v90, v90, v174, vcc
	v_cmp_gt_i32_e32 vcc, 42, v82
	v_cmp_lt_i32_e64 s[4:5], 42, v83
	s_or_b64 vcc, vcc, s[4:5]
	v_cndmask_b32_e32 v73, v73, v174, vcc
	v_cmp_gt_i32_e32 vcc, 11, v82
	v_cmp_lt_i32_e64 s[4:5], 11, v83
	s_or_b64 vcc, vcc, s[4:5]
	v_cndmask_b32_e32 v91, v91, v174, vcc
	v_cmp_gt_i32_e32 vcc, 43, v82
	v_cmp_lt_i32_e64 s[4:5], 43, v83
	s_or_b64 vcc, vcc, s[4:5]
	v_cndmask_b32_e32 v78, v78, v174, vcc
	v_cmp_gt_i32_e32 vcc, 16, v82
	v_cmp_lt_i32_e64 s[4:5], 16, v83
	s_or_b64 vcc, vcc, s[4:5]
	v_cndmask_b32_e32 v92, v92, v174, vcc
	v_cmp_gt_i32_e32 vcc, 48, v82
	v_cmp_lt_i32_e64 s[4:5], 48, v83
	s_or_b64 vcc, vcc, s[4:5]
	v_cndmask_b32_e32 v79, v79, v174, vcc
	v_cmp_gt_i32_e32 vcc, 17, v82
	v_cmp_lt_i32_e64 s[4:5], 17, v83
	s_or_b64 vcc, vcc, s[4:5]
	v_cndmask_b32_e32 v93, v93, v174, vcc
	v_cmp_gt_i32_e32 vcc, 49, v82
	v_cmp_lt_i32_e64 s[4:5], 49, v83
	s_or_b64 vcc, vcc, s[4:5]
	v_cndmask_b32_e32 v74, v74, v174, vcc
	v_cmp_gt_i32_e32 vcc, 18, v82
	v_cmp_lt_i32_e64 s[4:5], 18, v83
	s_or_b64 vcc, vcc, s[4:5]
	v_cndmask_b32_e32 v94, v94, v174, vcc
	v_cmp_gt_i32_e32 vcc, 50, v82
	v_cmp_lt_i32_e64 s[4:5], 50, v83
	s_or_b64 vcc, vcc, s[4:5]
	v_cndmask_b32_e32 v75, v75, v174, vcc
	v_cmp_gt_i32_e32 vcc, 19, v82
	v_cmp_lt_i32_e64 s[4:5], 19, v83
	s_or_b64 vcc, vcc, s[4:5]
	v_cndmask_b32_e32 v95, v95, v174, vcc
	v_cmp_gt_i32_e32 vcc, 51, v82
	v_cmp_lt_i32_e64 s[4:5], 51, v83
	s_or_b64 vcc, vcc, s[4:5]
	v_cndmask_b32_e32 v68, v68, v174, vcc
	v_cmp_gt_i32_e32 vcc, 24, v82
	v_cmp_lt_i32_e64 s[4:5], 24, v83
	s_or_b64 vcc, vcc, s[4:5]
	v_cndmask_b32_e32 v96, v96, v174, vcc
	v_cmp_gt_i32_e32 vcc, 56, v82
	v_cmp_lt_i32_e64 s[4:5], 56, v83
	s_or_b64 vcc, vcc, s[4:5]
	v_cndmask_b32_e32 v69, v69, v174, vcc
	v_cmp_gt_i32_e32 vcc, 25, v82
	v_cmp_lt_i32_e64 s[4:5], 25, v83
	s_or_b64 vcc, vcc, s[4:5]
	v_cndmask_b32_e32 v97, v97, v174, vcc
	v_cmp_gt_i32_e32 vcc, 57, v82
	v_cmp_lt_i32_e64 s[4:5], 57, v83
	s_or_b64 vcc, vcc, s[4:5]
	v_cndmask_b32_e32 v70, v70, v174, vcc
	v_cmp_gt_i32_e32 vcc, 26, v82
	v_cmp_lt_i32_e64 s[4:5], 26, v83
	s_or_b64 vcc, vcc, s[4:5]
	v_cndmask_b32_e32 v80, v80, v174, vcc
	v_cmp_gt_i32_e32 vcc, 58, v82
	v_cmp_lt_i32_e64 s[4:5], 58, v83
	s_or_b64 vcc, vcc, s[4:5]
	v_cndmask_b32_e32 v71, v71, v174, vcc
	v_cmp_gt_i32_e32 vcc, 27, v82
	v_cmp_lt_i32_e64 s[4:5], 27, v83
	s_or_b64 vcc, vcc, s[4:5]
	v_cndmask_b32_e32 v81, v81, v174, vcc
	v_cmp_gt_i32_e32 vcc, 59, v82
	v_cmp_lt_i32_e64 s[4:5], 59, v83
	s_or_b64 vcc, vcc, s[4:5]
	v_cndmask_b32_e32 v2, v2, v174, vcc

; __device__ __forceinline__ void qkt(f32x16& p0, f32x16& p1, const char* Ks, const bf16x8* qr, int r32, int hi) {
;   p0 = f32x16{}; p1 = f32x16{};
; #pragma unroll
;   for (int d0 = 0; d0 < 8; ++d0) { int cb = (d0 * 16 + hi * 8) * 2;
;     bf16x8 b0 = *reinterpret_cast<const bf16x8*>(Ks + KSWZ(r32, cb));
;     bf16x8 b1 = *reinterpret_cast<const bf16x8*>(Ks + KSWZ(32 + r32, cb));
;     p0 = __builtin_amdgcn_mfma_f32_32x32x16_bf16(b0, qr[d0], p0, 0, 0, 0);
;     p1 = __builtin_amdgcn_mfma_f32_32x32x16_bf16(b1, qr[d0], p1, 0, 0, 0); }
; __device__ __forceinline__ void score_xform(f32x16& p0, f32x16& p1, float sl, float base, bool mask, int kp0, int t, int tlo) {
;   const float s2_ = sl + sl, s4_ = s2_ + s2_, s8_ = s4_ + s4_;
;   const float a_[4] = {0.f, sl, s2_, s2_ + sl};
;   float b_[8]; b_[0] = base;
; #pragma unroll
;   for (int q = 1; q < 8; ++q) b_[q] = b_[q - 1] + s8_;
; #pragma unroll
;   for (int r = 0; r < 16; ++r) { p0[r] = fmaf(p0[r], CSC, a_[r & 3] + b_[r >> 2]); p1[r] = fmaf(p1[r], CSC, a_[r & 3] + b_[4 + (r >> 2)]); }
.LBB0_2427:
	s_add_i32 s4, s95, s9
	s_add_i32 m0, s4, 0xa000
	s_add_i32 s4, s8, 0
	global_load_lds_dwordx4 v[68:69], off
	v_add_u32_e32 v2, s4, v182
	ds_read_b128 v[68:71], v2
	ds_read_b128 v[72:75], v2 offset:8192
	v_add_u32_e32 v2, s4, v183
	ds_read_b128 v[164:167], v2
	ds_read_b128 v[168:171], v2 offset:8192
	v_add_u32_e32 v2, s4, v184
	ds_read_b128 v[240:243], v2
	ds_read_b128 v[244:247], v2 offset:8192
	v_lshl_add_u32 v199, s6, 6, v188
	s_cmp_lg_u32 s6, s97
	s_waitcnt lgkmcnt(4)
	v_mfma_f32_32x32x16_bf16 v[84:99], v[68:71], v[104:107], 0
	v_add_u32_e32 v2, s4, v185
	v_mfma_f32_32x32x16_bf16 v[68:83], v[72:75], v[104:107], 0
	s_waitcnt lgkmcnt(2)
	v_mfma_f32_32x32x16_bf16 v[84:99], v[164:167], v[108:111], v[84:99]
	v_mfma_f32_32x32x16_bf16 v[68:83], v[168:171], v[108:111], v[68:83]
	ds_read_b128 v[164:167], v2
	ds_read_b128 v[168:171], v2 offset:8192
	v_add_u32_e32 v2, s4, v186
	s_waitcnt lgkmcnt(2)
	v_mfma_f32_32x32x16_bf16 v[84:99], v[240:243], v[112:115], v[84:99]
	v_mfma_f32_32x32x16_bf16 v[68:83], v[244:247], v[112:115], v[68:83]
	ds_read_b128 v[240:243], v2
	ds_read_b128 v[244:247], v2 offset:8192
	v_add_u32_e32 v2, s4, v187
	s_waitcnt lgkmcnt(2)
	v_mfma_f32_32x32x16_bf16 v[84:99], v[164:167], v[116:119], v[84:99]
	v_mfma_f32_32x32x16_bf16 v[68:83], v[168:171], v[116:119], v[68:83]
	ds_read_b128 v[164:167], v2
	ds_read_b128 v[168:171], v2 offset:8192
	v_add_u32_e32 v2, s4, v189
	s_waitcnt lgkmcnt(2)
	v_mfma_f32_32x32x16_bf16 v[84:99], v[240:243], v[120:123], v[84:99]
	v_mfma_f32_32x32x16_bf16 v[68:83], v[244:247], v[120:123], v[68:83]
	ds_read_b128 v[240:243], v2
	ds_read_b128 v[244:247], v2 offset:8192
	v_add_u32_e32 v2, s4, v190
	s_waitcnt lgkmcnt(2)
	v_mfma_f32_32x32x16_bf16 v[84:99], v[164:167], v[124:127], v[84:99]
	v_mfma_f32_32x32x16_bf16 v[68:83], v[168:171], v[124:127], v[68:83]
	ds_read_b128 v[164:167], v2
	ds_read_b128 v[168:171], v2 offset:8192
	s_waitcnt lgkmcnt(2)
	v_mfma_f32_32x32x16_bf16 v[84:99], v[240:243], v[128:131], v[84:99]
	v_mfma_f32_32x32x16_bf16 v[68:83], v[244:247], v[128:131], v[68:83]
	v_bfe_u32 v2, v196, s6, 1
	v_cmp_eq_u32_e32 vcc, 0, v2
	v_sub_u32_e32 v2, v199, v181
	v_cvt_f32_i32_e32 v2, v2
	s_waitcnt lgkmcnt(0)
	v_mfma_f32_32x32x16_bf16 v[84:99], v[164:167], v[132:135], v[84:99]
	v_cndmask_b32_e32 v166, 0, v174, vcc
	v_fmac_f32_e32 v166, v141, v2
	v_mov_b32_e32 v2, v166
	v_add_f32_e64 v164, v146, v166
	v_add_f32_e64 v165, v147, v166
	v_mfma_f32_32x32x16_bf16 v[68:83], v[168:171], v[132:135], v[68:83]
	s_nop 5
	v_fmac_f32_e32 v2, 0x3e0293ee, v84
	v_mov_b32_e32 v84, v85
	v_mov_b32_e32 v85, v86
	v_fma_f32 v164, v84, s86, v164
	v_fma_f32 v165, v85, s86, v165
	v_pk_add_f32 v[84:85], v[144:145], v[166:167] op_sel_hi:[1,0]
	v_mov_b32_e32 v86, v87
	v_mov_b32_e32 v87, v88
	v_pk_fma_f32 v[166:167], v[86:87], s[86:87], v[84:85] op_sel_hi:[1,0,1]
	v_pk_add_f32 v[86:87], v[146:147], v[84:85] op_sel:[0,1]
	v_mov_b32_e32 v88, v89
	v_mov_b32_e32 v89, v90
	v_pk_add_f32 v[84:85], v[144:145], v[84:85] op_sel:[0,1]
	v_pk_fma_f32 v[168:169], v[88:89], s[86:87], v[86:87] op_sel_hi:[1,0,1]
	v_mov_b32_e32 v86, v91
	v_mov_b32_e32 v87, v92
	v_pk_add_f32 v[200:201], v[144:145], v[84:85] op_sel:[0,1]
	v_pk_fma_f32 v[170:171], v[86:87], s[86:87], v[84:85] op_sel_hi:[1,0,1]
	v_pk_add_f32 v[86:87], v[146:147], v[84:85] op_sel:[0,1]
	v_mov_b32_e32 v88, v93
	v_mov_b32_e32 v89, v94
	v_pk_add_f32 v[84:85], v[144:145], v[200:201]
	v_pk_fma_f32 v[92:93], v[88:89], s[86:87], v[86:87] op_sel_hi:[1,0,1]
	v_add_f32_e32 v87, v141, v85
	v_mov_b32_e32 v86, v85
	v_pk_add_f32 v[202:203], v[144:145], v[84:85]
	v_pk_fma_f32 v[90:91], v[68:69], s[86:87], v[86:87] op_sel_hi:[1,0,1]
	v_pk_add_f32 v[68:69], v[142:143], v[84:85] op_sel:[0,1]
	v_pk_add_f32 v[204:205], v[144:145], v[202:203]
	v_pk_fma_f32 v[88:89], v[70:71], s[86:87], v[68:69] op_sel_hi:[1,0,1]
	v_pk_add_f32 v[68:69], v[140:141], v[202:203] op_sel:[0,1]
	s_nop 0
	v_pk_fma_f32 v[86:87], v[72:73], s[86:87], v[68:69] op_sel_hi:[1,0,1]
	v_pk_add_f32 v[68:69], v[142:143], v[202:203] op_sel:[0,1]
	s_nop 0
	v_pk_fma_f32 v[84:85], v[74:75], s[86:87], v[68:69] op_sel_hi:[1,0,1]
	v_pk_add_f32 v[68:69], v[140:141], v[204:205] op_sel:[0,1]
	v_add_f32_e32 v74, v145, v205
	v_pk_fma_f32 v[70:71], v[76:77], s[86:87], v[68:69] op_sel_hi:[1,0,1]
	v_mov_b32_e32 v68, v95
	v_mov_b32_e32 v69, v96
	v_pk_fma_f32 v[76:77], v[68:69], s[86:87], v[200:201] op_sel_hi:[1,0,1]
	v_pk_add_f32 v[68:69], v[142:143], v[204:205] op_sel:[0,1]
	s_nop 0
	v_pk_fma_f32 v[72:73], v[78:79], s[86:87], v[68:69] op_sel_hi:[1,0,1]
	v_pk_add_f32 v[68:69], v[140:141], v[74:75] op_sel_hi:[1,0]
	v_pk_add_f32 v[78:79], v[146:147], v[200:201] op_sel:[0,1]
	v_pk_fma_f32 v[68:69], v[80:81], s[86:87], v[68:69] op_sel_hi:[1,0,1]
	v_mov_b32_e32 v80, v97
	v_mov_b32_e32 v81, v98
	v_pk_fma_f32 v[78:79], v[80:81], s[86:87], v[78:79] op_sel_hi:[1,0,1]
	v_add_f32_e32 v80, v144, v201
	v_pk_add_f32 v[74:75], v[142:143], v[74:75] op_sel_hi:[1,0]
	v_fmac_f32_e32 v80, 0x3e0293ee, v99
	v_pk_fma_f32 v[74:75], v[82:83], s[86:87], v[74:75] op_sel_hi:[1,0,1]
	s_cbranch_scc1 .LBB0_2429
; __device__ __forceinline__ void score_xform(f32x16& p0, f32x16& p1, float sl, float base, bool mask, int kp0, int t, int tlo) {
;     ...
;   if (mask) {
;     const int dhi = t - kp0, dlo = tlo - kp0;
; #pragma unroll
;     for (int r = 0; r < 16; ++r) { const int c = (r & 3) + 8 * (r >> 2);
;       p0[r] = (c > dhi || c < dlo) ? -1e30f : p0[r]; p1[r] = (c + 32 > dhi || c + 32 < dlo) ? -1e30f : p1[r]; } }
	v_sub_u32_e32 v81, v181, v199
	v_or_b32_e32 v82, v81, v199
	v_cmp_lt_i32_e32 vcc, -1, v82
	v_cmp_gt_i32_e64 s[6:7], 1, v81
	v_cmp_gt_i32_e64 s[4:5], -2, v199
	v_cndmask_b32_e32 v2, v174, v2, vcc
	v_cmp_gt_i32_e32 vcc, -1, v199
	v_cmp_gt_i32_e64 s[8:9], 2, v81
	s_or_b64 vcc, vcc, s[6:7]
	v_cndmask_b32_e32 v164, v164, v174, vcc
	s_or_b64 vcc, s[4:5], s[8:9]
	v_cndmask_b32_e32 v165, v165, v174, vcc
	v_cmp_gt_i32_e32 vcc, -3, v199
	v_cmp_gt_i32_e64 s[6:7], 3, v81
	v_cmp_gt_i32_e64 s[4:5], -8, v199
	v_cmp_gt_i32_e64 s[8:9], 8, v81
	s_or_b64 vcc, vcc, s[6:7]
	v_cndmask_b32_e32 v166, v166, v174, vcc
	s_or_b64 vcc, s[4:5], s[8:9]
	v_cndmask_b32_e32 v167, v167, v174, vcc
	v_cmp_gt_i32_e32 vcc, -9, v199
	v_cmp_gt_i32_e64 s[6:7], 9, v81
	v_cmp_gt_i32_e64 s[4:5], -10, v199
	v_cmp_gt_i32_e64 s[8:9], 10, v81
	s_or_b64 vcc, vcc, s[6:7]
	v_cndmask_b32_e32 v168, v168, v174, vcc
	s_or_b64 vcc, s[4:5], s[8:9]
	v_cndmask_b32_e32 v169, v169, v174, vcc
	v_cmp_gt_i32_e32 vcc, -11, v199
	v_cmp_gt_i32_e64 s[6:7], 11, v81
	v_cmp_gt_i32_e64 s[4:5], -16, v199
	v_cmp_gt_i32_e64 s[8:9], 16, v81
	s_or_b64 vcc, vcc, s[6:7]
	v_cndmask_b32_e32 v170, v170, v174, vcc
	s_or_b64 vcc, s[4:5], s[8:9]
	s_movk_i32 s4, 0xffef
	v_cndmask_b32_e32 v171, v171, v174, vcc
	v_cmp_gt_i32_e32 vcc, s4, v199
	s_movk_i32 s4, 0xffee
	v_cmp_gt_i32_e64 s[6:7], 17, v81
	v_cmp_gt_i32_e64 s[4:5], s4, v199
	v_cmp_gt_i32_e64 s[8:9], 18, v81
	s_or_b64 vcc, vcc, s[6:7]
	v_cndmask_b32_e32 v92, v92, v174, vcc
	s_or_b64 vcc, s[4:5], s[8:9]
	s_movk_i32 s4, 0xffed
	v_cndmask_b32_e32 v93, v93, v174, vcc
	v_cmp_gt_i32_e32 vcc, s4, v199
	s_movk_i32 s4, 0xffe8
	v_cmp_gt_i32_e64 s[6:7], 19, v81
	v_cmp_gt_i32_e64 s[4:5], s4, v199
	v_cmp_gt_i32_e64 s[8:9], 24, v81
	s_or_b64 vcc, vcc, s[6:7]
	v_cndmask_b32_e32 v76, v76, v174, vcc
	s_or_b64 vcc, s[4:5], s[8:9]
	s_movk_i32 s4, 0xffe7
	v_cndmask_b32_e32 v77, v77, v174, vcc
	v_cmp_gt_i32_e32 vcc, s4, v199
	s_movk_i32 s4, 0xffe6
	v_cmp_gt_i32_e64 s[6:7], 25, v81
	v_cmp_gt_i32_e64 s[4:5], s4, v199
	v_cmp_gt_i32_e64 s[8:9], 26, v81
	s_or_b64 vcc, vcc, s[6:7]
	v_cndmask_b32_e32 v78, v78, v174, vcc
	s_or_b64 vcc, s[4:5], s[8:9]
	s_movk_i32 s4, 0xffe5
	v_cndmask_b32_e32 v79, v79, v174, vcc
	v_cmp_gt_i32_e32 vcc, 27, v81
	v_cmp_gt_i32_e64 s[4:5], s4, v199
	s_or_b64 vcc, s[4:5], vcc
	s_movk_i32 s4, 0xffe0
	v_cndmask_b32_e32 v80, v80, v174, vcc
	v_cmp_gt_i32_e32 vcc, s4, v199
	s_movk_i32 s4, 0xffdf
	v_cmp_gt_i32_e64 s[36:37], 32, v81
	v_cmp_gt_i32_e64 s[4:5], s4, v199
	s_movk_i32 s6, 0xffde
	v_cmp_gt_i32_e64 s[38:39], 33, v81
	s_or_b64 vcc, vcc, s[36:37]
	v_cmp_gt_i32_e64 s[6:7], s6, v199
	s_movk_i32 s8, 0xffdd
	v_cmp_gt_i32_e64 s[40:41], 34, v81
	v_cndmask_b32_e32 v90, v90, v174, vcc
	s_or_b64 vcc, s[4:5], s[38:39]
	v_cmp_gt_i32_e64 s[8:9], s8, v199
	s_movk_i32 s10, 0xffd8
	v_cmp_gt_i32_e64 s[42:43], 35, v81
	v_cndmask_b32_e32 v91, v91, v174, vcc
	s_or_b64 vcc, s[6:7], s[40:41]
	v_cmp_gt_i32_e64 s[10:11], s10, v199
	s_movk_i32 s12, 0xffd7
	v_cmp_gt_i32_e64 s[44:45], 40, v81
	v_cndmask_b32_e32 v88, v88, v174, vcc
	s_or_b64 vcc, s[8:9], s[42:43]
	v_cmp_gt_i32_e64 s[12:13], s12, v199
	s_movk_i32 s14, 0xffd6
	v_cmp_gt_i32_e64 s[46:47], 41, v81
	v_cndmask_b32_e32 v89, v89, v174, vcc
	s_or_b64 vcc, s[10:11], s[44:45]
	v_cmp_gt_i32_e64 s[14:15], s14, v199
	s_movk_i32 s16, 0xffd5
	v_cmp_gt_i32_e64 s[48:49], 42, v81
	v_cndmask_b32_e32 v86, v86, v174, vcc
	s_or_b64 vcc, s[12:13], s[46:47]
	v_cmp_gt_i32_e64 s[16:17], s16, v199
	s_movk_i32 s18, 0xffd0
	v_cmp_gt_i32_e64 s[50:51], 43, v81
	v_cndmask_b32_e32 v87, v87, v174, vcc
	s_or_b64 vcc, s[14:15], s[48:49]
	v_cmp_gt_i32_e64 s[18:19], s18, v199
	s_movk_i32 s20, 0xffcf
	v_cmp_gt_i32_e64 s[52:53], 48, v81
	v_cndmask_b32_e32 v84, v84, v174, vcc
	s_or_b64 vcc, s[16:17], s[50:51]
	v_cmp_gt_i32_e64 s[20:21], s20, v199
	s_movk_i32 s22, 0xffce
	v_cmp_gt_i32_e64 s[54:55], 49, v81
	v_cndmask_b32_e32 v85, v85, v174, vcc
	s_or_b64 vcc, s[18:19], s[52:53]
	v_cmp_gt_i32_e64 s[22:23], s22, v199
	s_movk_i32 s24, 0xffcd
	v_cmp_gt_i32_e64 s[56:57], 50, v81
	v_cndmask_b32_e32 v70, v70, v174, vcc
	s_or_b64 vcc, s[20:21], s[54:55]
	v_cmp_gt_i32_e64 s[24:25], s24, v199
	s_movk_i32 s26, 0xffc8
	v_cmp_gt_i32_e64 s[58:59], 51, v81
	v_cndmask_b32_e32 v71, v71, v174, vcc
	s_or_b64 vcc, s[22:23], s[56:57]
	v_cmp_gt_i32_e64 s[26:27], s26, v199
	s_movk_i32 s28, 0xffc7
	v_cmp_gt_i32_e64 s[60:61], 56, v81
	v_cndmask_b32_e32 v72, v72, v174, vcc
	s_or_b64 vcc, s[24:25], s[58:59]
	v_cmp_gt_i32_e64 s[28:29], s28, v199
	s_movk_i32 s30, 0xffc6
	v_cmp_gt_i32_e64 s[62:63], 57, v81
	v_cndmask_b32_e32 v73, v73, v174, vcc
	s_or_b64 vcc, s[26:27], s[60:61]
	v_cmp_gt_i32_e64 s[30:31], s30, v199
	s_movk_i32 s34, 0xffc5
	v_cmp_gt_i32_e64 s[64:65], 58, v81
	v_cndmask_b32_e32 v68, v68, v174, vcc
	s_or_b64 vcc, s[28:29], s[62:63]
	v_cmp_gt_i32_e64 s[34:35], s34, v199
	v_cmp_gt_i32_e64 s[66:67], 59, v81
	v_cndmask_b32_e32 v69, v69, v174, vcc
	s_or_b64 vcc, s[30:31], s[64:65]
	v_cndmask_b32_e32 v74, v74, v174, vcc
	s_or_b64 vcc, s[34:35], s[66:67]
	v_cndmask_b32_e32 v75, v75, v174, vcc

; __device__ __forceinline__ void qkt(f32x16& p0, f32x16& p1, const char* Ks, const bf16x8* qr, int r32, int hi) {
;   p0 = f32x16{}; p1 = f32x16{};
; #pragma unroll
;   for (int d0 = 0; d0 < 8; ++d0) { int cb = (d0 * 16 + hi * 8) * 2;
;     bf16x8 b0 = *reinterpret_cast<const bf16x8*>(Ks + KSWZ(r32, cb));
;     bf16x8 b1 = *reinterpret_cast<const bf16x8*>(Ks + KSWZ(32 + r32, cb));
;     p0 = __builtin_amdgcn_mfma_f32_32x32x16_bf16(b0, qr[d0], p0, 0, 0, 0);
;     p1 = __builtin_amdgcn_mfma_f32_32x32x16_bf16(b1, qr[d0], p1, 0, 0, 0); }
; __device__ __forceinline__ void score_xform(f32x16& p0, f32x16& p1, float sl, float base, bool mask, int kp0, int t, int tlo) {
;   const float s2_ = sl + sl, s4_ = s2_ + s2_, s8_ = s4_ + s4_;
;   const float a_[4] = {0.f, sl, s2_, s2_ + sl};
;   float b_[8]; b_[0] = base;
; #pragma unroll
;   for (int q = 1; q < 8; ++q) b_[q] = b_[q - 1] + s8_;
; #pragma unroll
;   for (int r = 0; r < 16; ++r) { p0[r] = fmaf(p0[r], CSC, a_[r & 3] + b_[r >> 2]); p1[r] = fmaf(p1[r], CSC, a_[r & 3] + b_[4 + (r >> 2)]); }
.LBB0_2443:
	s_add_i32 s4, s8, 0
	v_add_u32_e32 v2, s4, v182
	ds_read_b128 v[68:71], v2
	ds_read_b128 v[72:75], v2 offset:8192
	v_add_u32_e32 v2, s4, v183
	ds_read_b128 v[158:161], v2
	ds_read_b128 v[162:165], v2 offset:8192
	v_add_u32_e32 v2, s4, v184
	ds_read_b128 v[240:243], v2
	ds_read_b128 v[244:247], v2 offset:8192
	s_lshl_b32 s7, s6, 6
	s_cmp_eq_u32 s6, s97
	s_waitcnt lgkmcnt(4)
	v_mfma_f32_32x32x16_bf16 v[84:99], v[68:71], v[104:107], 0
	v_add_u32_e32 v2, s4, v185
	v_mfma_f32_32x32x16_bf16 v[68:83], v[72:75], v[104:107], 0
	s_waitcnt lgkmcnt(2)
	v_mfma_f32_32x32x16_bf16 v[84:99], v[158:161], v[108:111], v[84:99]
	v_mfma_f32_32x32x16_bf16 v[68:83], v[162:165], v[108:111], v[68:83]
	ds_read_b128 v[158:161], v2
	ds_read_b128 v[162:165], v2 offset:8192
	v_add_u32_e32 v2, s4, v186
	s_waitcnt lgkmcnt(2)
	v_mfma_f32_32x32x16_bf16 v[84:99], v[240:243], v[112:115], v[84:99]
	v_mfma_f32_32x32x16_bf16 v[68:83], v[244:247], v[112:115], v[68:83]
	ds_read_b128 v[240:243], v2
	ds_read_b128 v[244:247], v2 offset:8192
	v_add_u32_e32 v2, s4, v187
	s_waitcnt lgkmcnt(2)
	v_mfma_f32_32x32x16_bf16 v[84:99], v[158:161], v[116:119], v[84:99]
	v_mfma_f32_32x32x16_bf16 v[68:83], v[162:165], v[116:119], v[68:83]
	ds_read_b128 v[158:161], v2
	ds_read_b128 v[162:165], v2 offset:8192
	v_add_u32_e32 v2, s4, v189
	s_waitcnt lgkmcnt(2)
	v_mfma_f32_32x32x16_bf16 v[84:99], v[240:243], v[120:123], v[84:99]
	v_mfma_f32_32x32x16_bf16 v[68:83], v[244:247], v[120:123], v[68:83]
	ds_read_b128 v[240:243], v2
	ds_read_b128 v[244:247], v2 offset:8192
	v_add_u32_e32 v2, s4, v190
	s_waitcnt lgkmcnt(2)
	v_mfma_f32_32x32x16_bf16 v[84:99], v[158:161], v[124:127], v[84:99]
	v_mfma_f32_32x32x16_bf16 v[68:83], v[162:165], v[124:127], v[68:83]
	ds_read_b128 v[166:169], v2
	s_cselect_b64 s[4:5], -1, 0
	s_cmp_lt_i32 s7, s33
	s_waitcnt lgkmcnt(1)
	v_mfma_f32_32x32x16_bf16 v[84:99], v[240:243], v[128:131], v[84:99]
	v_add_u32_e32 v159, s7, v188
	s_cselect_b64 s[6:7], -1, 0
	s_or_b64 s[4:5], s[4:5], s[6:7]
	s_andn2_b64 vcc, exec, s[4:5]
	v_mfma_f32_32x32x16_bf16 v[68:83], v[244:247], v[128:131], v[68:83]
	ds_read_b128 v[160:163], v2 offset:8192
	v_sub_u32_e32 v2, v159, v181
	v_cvt_f32_i32_e32 v2, v2
	v_fma_f32 v164, v141, v2, 0
	s_waitcnt lgkmcnt(1)
	v_mfma_f32_32x32x16_bf16 v[84:99], v[166:169], v[132:135], v[84:99]
	v_add_f32_e32 v165, v141, v164
	s_waitcnt lgkmcnt(0)
	v_mfma_f32_32x32x16_bf16 v[68:83], v[160:163], v[132:135], v[68:83]
	s_nop 8
	v_fma_f32 v154, v84, s86, v164
	v_fma_f32 v155, v85, s86, v165
	v_add_f32_e64 v84, v142, v164
	v_add_f32_e64 v85, v143, v164
	v_fma_f32 v86, v86, s86, v84
	v_fma_f32 v87, v87, s86, v85
	v_add_f32_e32 v84, v145, v164
	v_add_f32_e32 v85, v141, v84
	v_pk_fma_f32 v[88:89], v[88:89], s[86:87], v[84:85] op_sel_hi:[1,0,1]
	v_pk_add_f32 v[162:163], v[142:143], v[84:85] op_sel_hi:[1,0]
	v_add_f32_e32 v84, v145, v84
	v_add_f32_e32 v85, v141, v84
	v_mov_b32_e32 v161, v72
	v_mov_b32_e32 v72, v73
	v_mov_b32_e32 v73, v74
	v_pk_fma_f32 v[90:91], v[90:91], s[86:87], v[162:163] op_sel_hi:[1,0,1]
	v_mov_b32_e32 v74, v75
	v_mov_b32_e32 v75, v76
	v_mov_b32_e32 v162, v77
	v_pk_add_f32 v[76:77], v[142:143], v[84:85] op_sel_hi:[1,0]
	v_add_f32_e32 v166, v145, v84
	v_pk_fma_f32 v[94:95], v[94:95], s[86:87], v[76:77] op_sel_hi:[1,0,1]
	v_add_f32_e32 v76, v145, v166
	v_add_f32_e32 v77, v141, v76
	v_mov_b32_e32 v160, v71
	v_pk_fma_f32 v[92:93], v[92:93], s[86:87], v[84:85] op_sel_hi:[1,0,1]
	v_pk_fma_f32 v[84:85], v[68:69], s[86:87], v[76:77] op_sel_hi:[1,0,1]
	v_add_f32_e32 v158, v142, v76
	v_pk_add_f32 v[68:69], v[144:145], v[76:77] op_sel_hi:[1,0]
	v_fmac_f32_e32 v158, 0x3e0293ee, v70
	v_pk_fma_f32 v[76:77], v[160:161], s[86:87], v[68:69] op_sel_hi:[1,0,1]
	v_pk_add_f32 v[70:71], v[146:147], v[68:69] op_sel:[0,1]
	v_mov_b32_e32 v2, v69
	v_pk_add_f32 v[68:69], v[144:145], v[68:69]
	v_pk_fma_f32 v[72:73], v[72:73], s[86:87], v[70:71] op_sel_hi:[1,0,1]
	v_mov_b32_e32 v70, v144
	v_mov_b32_e32 v71, v69
	v_pk_add_f32 v[70:71], v[70:71], v[2:3]
	v_mov_b32_e32 v163, v78
	v_mov_b32_e32 v164, v79
	v_pk_add_f32 v[160:161], v[144:145], v[68:69]
	v_pk_fma_f32 v[78:79], v[74:75], s[86:87], v[70:71] op_sel_hi:[1,0,1]
	v_pk_add_f32 v[70:71], v[146:147], v[68:69] op_sel:[0,1]
	v_mov_b32_e32 v165, v80
	v_add_f32_e32 v167, v141, v166
	v_pk_fma_f32 v[74:75], v[162:163], s[86:87], v[70:71] op_sel_hi:[1,0,1]
	v_mov_b32_e32 v68, v69
	v_mov_b32_e32 v69, v161
	v_pk_add_f32 v[70:71], v[146:147], v[160:161] op_sel:[0,1]
	v_mov_b32_e32 v80, v81
	v_mov_b32_e32 v81, v82
	v_pk_add_f32 v[68:69], v[152:153], v[68:69]
	v_pk_fma_f32 v[70:71], v[80:81], s[86:87], v[70:71] op_sel_hi:[1,0,1]
	v_pk_add_f32 v[80:81], v[142:143], v[166:167] op_sel_hi:[1,0]
	v_add_f32_e32 v2, v144, v161
	v_pk_fma_f32 v[96:97], v[96:97], s[86:87], v[166:167] op_sel_hi:[1,0,1]
	v_pk_fma_f32 v[68:69], v[164:165], s[86:87], v[68:69] op_sel_hi:[1,0,1]
	v_pk_fma_f32 v[80:81], v[98:99], s[86:87], v[80:81] op_sel_hi:[1,0,1]
	v_fmac_f32_e32 v2, 0x3e0293ee, v83
	s_cbranch_vccnz .LBB0_2445
; __device__ __forceinline__ void score_xform(f32x16& p0, f32x16& p1, float sl, float base, bool mask, int kp0, int t, int tlo) {
;     ...
;   if (mask) {
;     const int dhi = t - kp0, dlo = tlo - kp0;
; #pragma unroll
;     for (int r = 0; r < 16; ++r) { const int c = (r & 3) + 8 * (r >> 2);
;       p0[r] = (c > dhi || c < dlo) ? -1e30f : p0[r]; p1[r] = (c + 32 > dhi || c + 32 < dlo) ? -1e30f : p1[r]; } }
	v_sub_u32_e32 v82, v181, v159
	v_sub_u32_e32 v83, v140, v159
	v_cmp_gt_i32_e32 vcc, 0, v82
	v_cmp_lt_i32_e64 s[4:5], 0, v83
	s_or_b64 vcc, vcc, s[4:5]
	v_cndmask_b32_e32 v154, v154, v174, vcc
	v_cmp_gt_i32_e32 vcc, 32, v82
	v_cmp_lt_i32_e64 s[4:5], 32, v83
	s_or_b64 vcc, vcc, s[4:5]
	v_cndmask_b32_e32 v84, v84, v174, vcc
	v_cmp_gt_i32_e32 vcc, 1, v82
	v_cmp_lt_i32_e64 s[4:5], 1, v83
	s_or_b64 vcc, vcc, s[4:5]
	v_cndmask_b32_e32 v155, v155, v174, vcc
	v_cmp_gt_i32_e32 vcc, 33, v82
	v_cmp_lt_i32_e64 s[4:5], 33, v83
	s_or_b64 vcc, vcc, s[4:5]
	v_cndmask_b32_e32 v85, v85, v174, vcc
	v_cmp_gt_i32_e32 vcc, 2, v82
	v_cmp_lt_i32_e64 s[4:5], 2, v83
	s_or_b64 vcc, vcc, s[4:5]
	v_cndmask_b32_e32 v86, v86, v174, vcc
	v_cmp_gt_i32_e32 vcc, 34, v82
	v_cmp_lt_i32_e64 s[4:5], 34, v83
	s_or_b64 vcc, vcc, s[4:5]
	v_cndmask_b32_e32 v158, v158, v174, vcc
	v_cmp_gt_i32_e32 vcc, 3, v82
	v_cmp_lt_i32_e64 s[4:5], 3, v83
	s_or_b64 vcc, vcc, s[4:5]
	v_cndmask_b32_e32 v87, v87, v174, vcc
	v_cmp_gt_i32_e32 vcc, 8, v82
	v_cmp_lt_i32_e64 s[4:5], 8, v83
	s_or_b64 vcc, vcc, s[4:5]
	v_cndmask_b32_e32 v88, v88, v174, vcc
	v_cmp_gt_i32_e32 vcc, 35, v82
	v_cmp_lt_i32_e64 s[6:7], 35, v83
	v_cmp_gt_i32_e64 s[4:5], 40, v82
	v_cmp_lt_i32_e64 s[8:9], 40, v83
	s_or_b64 vcc, vcc, s[6:7]
	v_cndmask_b32_e32 v76, v76, v174, vcc
	s_or_b64 vcc, s[4:5], s[8:9]
	v_cndmask_b32_e32 v77, v77, v174, vcc
	v_cmp_gt_i32_e32 vcc, 9, v82
	v_cmp_lt_i32_e64 s[4:5], 9, v83
	s_or_b64 vcc, vcc, s[4:5]
	v_cndmask_b32_e32 v89, v89, v174, vcc
	v_cmp_gt_i32_e32 vcc, 41, v82
	v_cmp_lt_i32_e64 s[4:5], 41, v83
	s_or_b64 vcc, vcc, s[4:5]
	v_cndmask_b32_e32 v72, v72, v174, vcc
	v_cmp_gt_i32_e32 vcc, 10, v82
	v_cmp_lt_i32_e64 s[4:5], 10, v83
	s_or_b64 vcc, vcc, s[4:5]
	v_cndmask_b32_e32 v90, v90, v174, vcc
	v_cmp_gt_i32_e32 vcc, 42, v82
	v_cmp_lt_i32_e64 s[4:5], 42, v83
	s_or_b64 vcc, vcc, s[4:5]
	v_cndmask_b32_e32 v73, v73, v174, vcc
	v_cmp_gt_i32_e32 vcc, 11, v82
	v_cmp_lt_i32_e64 s[4:5], 11, v83
	s_or_b64 vcc, vcc, s[4:5]
	v_cndmask_b32_e32 v91, v91, v174, vcc
	v_cmp_gt_i32_e32 vcc, 43, v82
	v_cmp_lt_i32_e64 s[4:5], 43, v83
	s_or_b64 vcc, vcc, s[4:5]
	v_cndmask_b32_e32 v78, v78, v174, vcc
	v_cmp_gt_i32_e32 vcc, 16, v82
	v_cmp_lt_i32_e64 s[4:5], 16, v83
	s_or_b64 vcc, vcc, s[4:5]
	v_cndmask_b32_e32 v92, v92, v174, vcc
	v_cmp_gt_i32_e32 vcc, 48, v82
	v_cmp_lt_i32_e64 s[4:5], 48, v83
	s_or_b64 vcc, vcc, s[4:5]
	v_cndmask_b32_e32 v79, v79, v174, vcc
	v_cmp_gt_i32_e32 vcc, 17, v82
	v_cmp_lt_i32_e64 s[4:5], 17, v83
	s_or_b64 vcc, vcc, s[4:5]
	v_cndmask_b32_e32 v93, v93, v174, vcc
	v_cmp_gt_i32_e32 vcc, 49, v82
	v_cmp_lt_i32_e64 s[4:5], 49, v83
	s_or_b64 vcc, vcc, s[4:5]
	v_cndmask_b32_e32 v74, v74, v174, vcc
	v_cmp_gt_i32_e32 vcc, 18, v82
	v_cmp_lt_i32_e64 s[4:5], 18, v83
	s_or_b64 vcc, vcc, s[4:5]
	v_cndmask_b32_e32 v94, v94, v174, vcc
	v_cmp_gt_i32_e32 vcc, 50, v82
	v_cmp_lt_i32_e64 s[4:5], 50, v83
	s_or_b64 vcc, vcc, s[4:5]
	v_cndmask_b32_e32 v75, v75, v174, vcc
	v_cmp_gt_i32_e32 vcc, 19, v82
	v_cmp_lt_i32_e64 s[4:5], 19, v83
	s_or_b64 vcc, vcc, s[4:5]
	v_cndmask_b32_e32 v95, v95, v174, vcc
	v_cmp_gt_i32_e32 vcc, 51, v82
	v_cmp_lt_i32_e64 s[4:5], 51, v83
	s_or_b64 vcc, vcc, s[4:5]
	v_cndmask_b32_e32 v68, v68, v174, vcc
	v_cmp_gt_i32_e32 vcc, 24, v82
	v_cmp_lt_i32_e64 s[4:5], 24, v83
	s_or_b64 vcc, vcc, s[4:5]
	v_cndmask_b32_e32 v96, v96, v174, vcc
	v_cmp_gt_i32_e32 vcc, 56, v82
	v_cmp_lt_i32_e64 s[4:5], 56, v83
	s_or_b64 vcc, vcc, s[4:5]
	v_cndmask_b32_e32 v69, v69, v174, vcc
	v_cmp_gt_i32_e32 vcc, 25, v82
	v_cmp_lt_i32_e64 s[4:5], 25, v83
	s_or_b64 vcc, vcc, s[4:5]
	v_cndmask_b32_e32 v97, v97, v174, vcc
	v_cmp_gt_i32_e32 vcc, 57, v82
	v_cmp_lt_i32_e64 s[4:5], 57, v83
	s_or_b64 vcc, vcc, s[4:5]
	v_cndmask_b32_e32 v70, v70, v174, vcc
	v_cmp_gt_i32_e32 vcc, 26, v82
	v_cmp_lt_i32_e64 s[4:5], 26, v83
	s_or_b64 vcc, vcc, s[4:5]
	v_cndmask_b32_e32 v80, v80, v174, vcc
	v_cmp_gt_i32_e32 vcc, 58, v82
	v_cmp_lt_i32_e64 s[4:5], 58, v83
	s_or_b64 vcc, vcc, s[4:5]
	v_cndmask_b32_e32 v71, v71, v174, vcc
	v_cmp_gt_i32_e32 vcc, 27, v82
	v_cmp_lt_i32_e64 s[4:5], 27, v83
	s_or_b64 vcc, vcc, s[4:5]
	v_cndmask_b32_e32 v81, v81, v174, vcc
	v_cmp_gt_i32_e32 vcc, 59, v82
	v_cmp_lt_i32_e64 s[4:5], 59, v83
	s_or_b64 vcc, vcc, s[4:5]
	v_cndmask_b32_e32 v2, v2, v174, vcc
